# PIN5: per-loop placement pin: attention + FFT phase code moved to the other 8-byte phase, GEMM1/GEMM2 as in the final
# baseline (speedup 1.0000x reference)
;     __device__ bool next(int i, Unit& u) const { const long L = (long)i * G + c; if (L >= hi) return false; unit_of((int)L, u); return true; }
; #define PG8_STAGE(bufoff, gbase) do { _Pragma("unroll") for (int _i = 0; _i < 2; ++_i) \
;         __builtin_amdgcn_global_load_lds((const unsigned*)((const char*)(gbase) + voffA[_i]), (LAS unsigned*)(lds + (bufoff) + ldsw + _i * 8192), 16, 0, 0); } while (0)
; template <class Epi, bool SPLITA>
; __device__ __forceinline__ void gemm_phase(LAS unsigned char* lds, const Gemm g, const StaticOrder& S, const Epi& E) {
;     ...
;     const int tid = tid_, wid = __builtin_amdgcn_readfirstlane(tid >> 6), lane = tid & 63, wr = wid >> 2, wc = wid & 3, fr = lane & 15, fq = lane >> 4;
;     const int K = g.K, nt = K / BK;
;     unsigned voffA[2], voffF[2], voffM[2];
; #pragma unroll
;     for (int i = 0; i < 2; ++i) { int R, C; stage_rc(tid * 16 + i * 8192, R, C); voffA[i] = (unsigned)(R * K + C) * 2u; voffF[i] = (unsigned)((C >> 3) * 65536 + R * 16); voffM[i] = (unsigned)(R * 512 + C) * 2u; }
;     const size_t kstep = (size_t)(BK * 2);
;     const size_t hstep = (size_t)HALF * K * 2;
;     const size_t tstep = 2 * hstep;
;     const unsigned ldsw = (unsigned)wid * 1024u;
;     const int aoff = lds_byte(wr * 64 + fr, fq * 8), boff = lds_byte(wc * 32 + fr, fq * 8);
;     ...
;     Unit cur, nxt; int ui = 0;
;     if (!S.next(0, cur)) return;
;     E.prepare(lds, S, tid);
;     f32x4 acc[2][2][4][2];
; #pragma unroll
;     for (int a = 0; a < 2; ++a)
; #pragma unroll
;         for (int b = 0; b < 2; ++b)
; #pragma unroll
;             for (int m = 0; m < 4; ++m)
; #pragma unroll
;                 for (int n = 0; n < 2; ++n) acc[a][b][m][n] = (f32x4){0.f, 0.f, 0.f, 0.f};
;     f16x8 At[4][2], B0[2][2], B1[2][2];
;     const char* cB = (const char*)g.Bt + (size_t)cur.pn * tstep;
;     PG8_STAGE(PG8_SB(0, 0), cB); PG8_STAGE(PG8_SB(0, 1), cB + hstep); PG8_STAGE_A(PG8_SA(0, 0), cur.pm, 0, 0); PG8_STAGE_A(PG8_SA(0, 1), cur.pm, 0, 1);
;     if (wr == 1) PG8_BAR;
; __device__ __forceinline__ void xcd_barrier(const XcdBarrier& b) {
;     ...
;             asm volatile("s_waitcnt vmcnt(0)" ::: "memory");
;         } else {
;             XB_SPIN(xb_ld(&bar[XB_XGEN(b.x)]) == gen, bar);
;             __builtin_amdgcn_fence(__ATOMIC_ACQUIRE, "agent");
;             asm volatile("s_waitcnt vmcnt(0)" ::: "memory");
;         }
;     }
;     __syncthreads();
.LBB0_471:
	s_or_b64 exec, exec, s[4:5]
	v_mov_b32_e32 v2, s8
	v_add_co_u32_e32 v2, vcc, 0x2000, v2
	v_mov_b32_e32 v3, s7
	s_nop 0
	v_addc_co_u32_e32 v3, vcc, 0, v3, vcc
	s_waitcnt vmcnt(0) lgkmcnt(0)
	buffer_inv sc1
	flat_atomic_add v[2:3], v224 offset:1024
	s_waitcnt vmcnt(0)
.LBB0_472:
	s_or_b64 exec, exec, s[0:1]
	s_waitcnt lgkmcnt(0)
	s_barrier
	s_nop 0
.LBB0_473:
	s_cmp_le_i32 s42, s6
	s_cselect_b64 s[4:5], -1, 0
	s_cmp_lt_i32 s6, s43
	s_cselect_b64 s[6:7], -1, 0
	s_and_b64 s[0:1], s[4:5], s[6:7]
	s_andn2_b64 vcc, exec, s[0:1]
	s_cbranch_vccnz .LBB0_508
	s_waitcnt vmcnt(0)
	v_mov_b32_e32 v2, v0
	s_andn2_b64 vcc, exec, s[92:93]
	v_readfirstlane_b32 s0, v2
	s_cbranch_vccnz .LBB0_508
	v_ashrrev_i32_e32 v3, 31, v2
	v_lshrrev_b32_e32 v3, 26, v3
	v_add_u32_e32 v3, v2, v3
	v_ashrrev_i32_e32 v4, 6, v3
	v_bfe_i32 v3, v2, 27, 1
	v_lshlrev_b32_e32 v5, 4, v2
	v_lshrrev_b32_e32 v3, 22, v3
	v_add_u32_e32 v3, v5, v3
	v_and_b32_e32 v3, 0xfffffc00, v3
	v_sub_u32_e32 v3, v5, v3
	v_lshrrev_b32_e32 v6, 4, v3
	v_bitop3_b32 v6, v6, v3, 32 bitop3:0x6c
	v_ashrrev_i32_e32 v7, 31, v6
	v_lshrrev_b32_e32 v7, 26, v7
	v_add_u32_e32 v7, v6, v7
	v_ashrrev_i32_e32 v8, 6, v7
	v_and_b32_e32 v7, 0xc0, v7
	v_lshlrev_b32_e32 v3, 3, v4
	v_lshlrev_b32_e32 v4, 5, v4
	v_sub_u32_e32 v6, v6, v7
	v_and_b32_e32 v4, 32, v4
	v_ashrrev_i16_sdwa v6, v224, sext(v6) dst_sel:DWORD dst_unused:UNUSED_PAD src0_sel:DWORD src1_sel:BYTE_0
	v_add_u32_e32 v5, 0x2000, v5
	v_add_u32_sdwa v4, v4, sext(v6) dst_sel:DWORD dst_unused:UNUSED_PAD src0_sel:DWORD src1_sel:WORD_0
	v_ashrrev_i32_e32 v6, 31, v5
	v_lshrrev_b32_e32 v6, 22, v6
	v_add_u32_e32 v6, v5, v6
	v_ashrrev_i32_e32 v6, 10, v6
	v_mul_i32_i24_e32 v7, 0x400, v6
	v_sub_u32_e32 v5, v5, v7
	v_lshrrev_b32_e32 v7, 4, v5
	v_and_b32_e32 v3, -16, v3
	v_bitop3_b32 v7, v7, v5, 32 bitop3:0x6c
	v_writelane_b32 v255, s6, 2
	v_add_u32_e32 v3, v8, v3
	v_ashrrev_i32_e32 v8, 31, v7
	v_writelane_b32 v255, s7, 3
	v_lshrrev_b32_e32 v8, 26, v8
	v_writelane_b32 v255, s4, 6
	v_add_u32_e32 v8, v7, v8
	s_lshl_b32 s1, s99, 21
	v_writelane_b32 v255, s5, 7
	v_readlane_b32 s4, v254, 19
	v_lshlrev_b32_e32 v5, 3, v6
	v_ashrrev_i32_e32 v9, 6, v8
	v_and_b32_e32 v8, 0xc0, v8
	s_add_u32 s8, s4, s1
	v_readlane_b32 s1, v254, 20
	v_and_b32_e32 v5, -16, v5
	v_lshlrev_b32_e32 v6, 5, v6
	v_sub_u32_e32 v7, v7, v8
	s_addc_u32 s9, s1, 0
	s_ashr_i32 s1, s0, 6
	v_add_u32_e32 v5, v9, v5
	v_and_b32_e32 v6, 32, v6
	v_ashrrev_i16_sdwa v7, v224, sext(v7) dst_sel:DWORD dst_unused:UNUSED_PAD src0_sel:DWORD src1_sel:BYTE_0
	v_add_u32_sdwa v6, v6, sext(v7) dst_sel:DWORD dst_unused:UNUSED_PAD src0_sel:DWORD src1_sel:WORD_0
	s_ashr_i32 s4, s0, 8
	s_lshl_b32 s5, s1, 10
	v_lshlrev_b32_e32 v7, 10, v5
	v_readlane_b32 s6, v254, 31
	v_lshl_add_u32 v200, v6, 1, v7
	v_readlane_b32 s7, v254, 32
	s_add_u32 s76, s8, s6
	v_add_u32_e32 v202, v200, v7
	v_lshlrev_b32_e32 v7, 10, v3
	s_addc_u32 s77, s9, s7
	s_add_i32 s12, s5, 0
	v_lshl_add_u32 v204, v4, 1, v7
	s_add_i32 s13, s12, 0x10000
	s_add_i32 s14, s12, 0x12000
	v_add_u32_e32 v194, v204, v7
	s_mov_b32 m0, s13
	s_add_u32 s6, s76, 0x40000
	global_load_lds_dwordx4 v194, s[76:77]
	s_mov_b32 m0, s14
	s_addc_u32 s7, s77, 0
	s_add_i32 s15, s12, 0x14000
	global_load_lds_dwordx4 v202, s[76:77]
	s_mov_b32 m0, s15
	s_add_i32 s31, s12, 0x16000
	global_load_lds_dwordx4 v194, s[6:7]
	s_mov_b32 m0, s31
	s_add_i32 s33, s12, 0x2000
	global_load_lds_dwordx4 v202, s[6:7]
	v_readlane_b32 s6, v254, 35
	s_mov_b32 m0, s12
	v_readlane_b32 s7, v254, 36
	s_add_i32 s36, s12, 0x4000
	s_add_i32 s37, s12, 0x6000
	s_load_dword s46, s[86:87], 0x0
	s_cmp_eq_u32 s4, 1
	s_nop 0
	global_load_lds_dwordx4 v204, s[6:7]
	s_mov_b32 m0, s33
	s_nop 0
	global_load_lds_dwordx4 v200, s[6:7]
	v_readlane_b32 s6, v254, 37
	s_mov_b32 m0, s36
	v_readlane_b32 s7, v254, 38
	s_nop 4
	global_load_lds_dwordx4 v204, s[6:7]
	s_mov_b32 m0, s37
	s_nop 0
	global_load_lds_dwordx4 v200, s[6:7]
	s_cselect_b64 s[6:7], -1, 0
	v_writelane_b32 v255, s6, 4
	s_cmp_lg_u32 s4, 1
	s_nop 0
	v_writelane_b32 v255, s7, 5
	s_cbranch_scc1 .LBB0_477
	s_barrier
